# software-pipelined NT=1 tail-tile K-loops (double-buffered fragments, interleaved loads/writes, peeled last iteration)
# speedup vs baseline: 1.0488x; 1.0003x over previous
; #define GLOAD(ra, rb, koff)                                                        \
;   {                                                                                \
;     _Pragma("unroll") for (int j = 0; j < 4; j++) ra[j] = *(const u32x4*)(pa + j * sa32 + (koff));   \
;     _Pragma("unroll") for (int j = 0; j < NB_; j++) rb[j] = *(const u32x4*)(pbv[j] + (koff));         \
;   }
; template <int NT, bool PRE> ...
;     ...
;   const int wsw = ((tid & 7) ^ ((tid >> 4) & 7)) * 8;
;   const int rsw = (lane & 15) >> 1;
;     ...
;   if (!PRE) {
;     GLOAD(ra0, rb0, 0);
;     GLOAD(ra1, rb1, 64);
;   }
;   __syncthreads();
;   for (int k0 = 0; k0 < K; k0 += 128) {
;     LSTORE(ra0, rb0, 0);
;     __syncthreads();
;     GLOAD(ra0, rb0, min(k0 + 128, K - 128));
;     __builtin_amdgcn_sched_barrier(0);
;     COMPUTE(0);
;     LSTORE(ra1, rb1, 1);
;     __syncthreads();
;     GLOAD(ra1, rb1, min(k0 + 192, K - 64));
;     __builtin_amdgcn_sched_barrier(0);
;     COMPUTE(1);
;   }
; template <int NT>
; __device__ __forceinline__ void gemm_main(const u16* __restrict__ A, int lda, const u16* __restrict__ Bt, int ldb,
;                                           int K, int m0, int n0, f32x4 (&acc)[4][NT], u16* sA, u16* sB) {
;     ...
;   const u16* pa = A + (size_t)(m0 + (tid >> 3)) * lda + (tid & 7) * 8;
;   const u16* pbv[NT];
; #pragma unroll
;   for (int j = 0; j < NT; j++) pbv[j] = Bt + (size_t)(n0 + (tid >> 3) + 32 * j) * ldb + (tid & 7) * 8;
.LBB0_584:
	v_readlane_b32 s0, v250, 35
	v_readlane_b32 s1, v250, 36
	s_and_b64 vcc, exec, s[0:1]
	s_cbranch_vccz .LBB0_771
	s_waitcnt vmcnt(4)
	v_mov_b32_e32 v8, v169
	v_readlane_b32 s0, v250, 42
	v_ashrrev_i32_e32 v4, 3, v8
	v_lshlrev_b32_e32 v9, 4, v8
	v_add_u32_e32 v2, s0, v4
	v_and_b32_e32 v130, 0x70, v9
	v_ashrrev_i32_e32 v3, 31, v2
	v_lshl_add_u64 v[0:1], s[14:15], 0, v[130:131]
	v_lshlrev_b64 v[2:3], 11, v[2:3]
	v_readlane_b32 s0, v250, 37
	v_lshl_add_u64 v[56:57], v[0:1], 0, v[2:3]
	v_mov_b32_e32 v12, 0
	v_add_u32_e32 v0, s0, v4
	v_ashrrev_i32_e32 v1, 31, v0
	v_lshlrev_b64 v[0:1], 11, v[0:1]
	v_lshl_add_u64 v[0:1], s[14:15], 0, v[0:1]
	v_lshl_add_u64 v[0:1], v[0:1], 0, v[130:131]
	s_mov_b64 s[0:1], 0x24cb800
	v_lshl_add_u64 v[58:59], v[0:1], 0, s[0:1]
	s_mov_b32 s0, 0x24cb000
	v_add_co_u32_e32 v2, vcc, s0, v0
	s_mov_b32 s0, 0x24db000
	s_nop 0
	v_addc_co_u32_e32 v3, vcc, 0, v1, vcc
	v_add_co_u32_e32 v4, vcc, s0, v0
	s_mov_b32 s0, 0x24eb000
	s_nop 0
	v_addc_co_u32_e32 v5, vcc, 0, v1, vcc
	v_add_co_u32_e32 v6, vcc, s0, v0
	s_mov_b32 s0, 0x24fb000
	s_nop 0
	v_addc_co_u32_e32 v7, vcc, 0, v1, vcc
	v_add_co_u32_e32 v0, vcc, s0, v0
	s_movk_i32 s0, 0xff80
	s_nop 0
	v_addc_co_u32_e32 v1, vcc, 0, v1, vcc
	global_load_dwordx4 v[24:27], v[2:3], off offset:2048
	global_load_dwordx4 v[36:39], v[58:59], off offset:128
	global_load_dwordx4 v[52:55], v[4:5], off offset:2048
	global_load_dwordx4 v[40:43], v[4:5], off offset:2176
	global_load_dwordx4 v[32:35], v[6:7], off offset:2048
	global_load_dwordx4 v[28:31], v[6:7], off offset:2176
	global_load_dwordx4 v[48:51], v[0:1], off offset:2048
	global_load_dwordx4 v[44:47], v[0:1], off offset:2176
	global_load_dwordx4 v[16:19], v[56:57], off
	global_load_dwordx4 v[20:23], v[56:57], off offset:128
	v_lshrrev_b32_e32 v0, 4, v8
	v_xor_b32_e32 v1, v0, v8
	v_lshlrev_b32_e32 v1, 4, v1
	v_bfe_u32 v3, v8, 1, 3
	v_and_b32_e32 v1, 0x70, v1
	v_and_or_b32 v60, v9, s0, v1
	v_bfe_u32 v1, v8, 4, 2
	v_bitop3_b32 v0, v0, v3, 3 bitop3:0x6c
	v_and_b32_e32 v2, 15, v8
	v_lshlrev_b32_e32 v62, 4, v0
	v_lshlrev_b32_e32 v0, 6, v8
	v_bitop3_b32 v1, v1, v3, 4 bitop3:0x36
	v_lshlrev_b32_e32 v4, 5, v8
	v_lshlrev_b32_e32 v2, 7, v2
	s_movk_i32 s1, 0x800
	v_and_b32_e32 v0, 0xffffe000, v0
	v_lshlrev_b32_e32 v63, 4, v1
	v_and_or_b32 v61, v4, s1, v2
	v_or_b32_e32 v4, v62, v0
	v_or_b32_e32 v0, v63, v0
	v_add_u32_e32 v64, v4, v2
	v_add_u32_e32 v65, v0, v2
	v_mov_b32_e32 v13, v12
	v_mov_b32_e32 v14, v12
	v_mov_b32_e32 v15, v12
	v_mov_b32_e32 v8, v12
	v_mov_b32_e32 v9, v12
	v_mov_b32_e32 v10, v12
	v_mov_b32_e32 v11, v12
	v_mov_b32_e32 v4, v12
	v_mov_b32_e32 v5, v12
	v_mov_b32_e32 v6, v12
	v_mov_b32_e32 v7, v12
	v_mov_b32_e32 v0, v12
	v_mov_b32_e32 v1, v12
	v_mov_b32_e32 v2, v12
	v_mov_b32_e32 v3, v12
	s_barrier
	s_waitcnt vmcnt(8)
	ds_write_b128 v60, v[24:27]
	s_waitcnt vmcnt(7)
	ds_write_b128 v60, v[52:55] offset:4096
	s_waitcnt vmcnt(5)
	ds_write_b128 v60, v[32:35] offset:8192
	s_waitcnt vmcnt(3)
	ds_write_b128 v60, v[48:51] offset:12288
	s_waitcnt vmcnt(1)
	ds_write_b128 v60, v[16:19] offset:16384
	s_waitcnt vmcnt(0)
	s_waitcnt lgkmcnt(0)
	s_barrier
.LBB0_586:
	s_add_i32 s1, s0, 0x100
	s_min_u32 s1, s1, 0x380
	s_lshl_b32 s54, s1, 1
	v_add_u32_e32 v86, v61, v62
	v_add_u32_e32 v87, v61, v63
	ds_read_b128 v[66:69], v64
	ds_read_b128 v[70:73], v64 offset:2048
	ds_read_b128 v[74:77], v64 offset:4096
	ds_read_b128 v[78:81], v64 offset:6144
	ds_read_b128 v[82:85], v86 offset:16384
	ds_read_b128 v[88:91], v65
	ds_read_b128 v[92:95], v65 offset:2048
	ds_read_b128 v[96:99], v65 offset:4096
	ds_read_b128 v[100:103], v65 offset:6144
	ds_read_b128 v[104:107], v87 offset:16384
	v_lshl_add_u64 v[24:25], v[58:59], 0, s[54:55]
	v_add_co_u32_e32 v32, vcc, s33, v24
	v_lshl_add_u64 v[16:17], v[56:57], 0, s[54:55]
	s_nop 0
	v_addc_co_u32_e32 v33, vcc, 0, v25, vcc
	v_add_co_u32_e32 v34, vcc, s56, v24
	s_nop 0
	s_nop 0
	v_addc_co_u32_e32 v35, vcc, 0, v25, vcc
	v_add_co_u32_e32 v48, vcc, s57, v24
	s_nop 0
	s_nop 0
	v_addc_co_u32_e32 v49, vcc, 0, v25, vcc
	s_addk_i32 s0, 0x80
	s_setprio 1
	s_waitcnt lgkmcnt(5)
	v_mfma_f32_16x16x32_bf16 v[12:15], v[82:85], v[66:69], v[12:15]
	global_load_dwordx4 v[16:19], v[16:17], off
	s_nop 0
	v_mfma_f32_16x16x32_bf16 v[8:11], v[82:85], v[70:73], v[8:11]
	global_load_dwordx4 v[24:27], v[24:25], off
	s_nop 0
	v_mfma_f32_16x16x32_bf16 v[4:7], v[82:85], v[74:77], v[4:7]
	global_load_dwordx4 v[52:55], v[32:33], off
	s_nop 0
	global_load_dwordx4 v[32:35], v[34:35], off
	s_nop 0
	v_mfma_f32_16x16x32_bf16 v[0:3], v[82:85], v[78:81], v[0:3]
	global_load_dwordx4 v[48:51], v[48:49], off
	s_nop 0
	s_waitcnt lgkmcnt(0)
	v_mfma_f32_16x16x32_bf16 v[12:15], v[104:107], v[88:91], v[12:15]
	s_waitcnt vmcnt(9)
	ds_write_b128 v60, v[20:23] offset:49152
	v_mfma_f32_16x16x32_bf16 v[8:11], v[104:107], v[92:95], v[8:11]
	s_waitcnt vmcnt(8)
	ds_write_b128 v60, v[36:39] offset:32768
	s_waitcnt vmcnt(7)
	ds_write_b128 v60, v[40:43] offset:36864
	v_mfma_f32_16x16x32_bf16 v[4:7], v[104:107], v[96:99], v[4:7]
	s_waitcnt vmcnt(6)
	ds_write_b128 v60, v[28:31] offset:40960
	v_mfma_f32_16x16x32_bf16 v[0:3], v[104:107], v[100:103], v[0:3]
	s_waitcnt vmcnt(5)
	ds_write_b128 v60, v[44:47] offset:45056
	s_setprio 0
	s_waitcnt lgkmcnt(0)
	s_barrier
; #define GLOAD(ra, rb, koff)                                                        \
;   {                                                                                \
;     _Pragma("unroll") for (int j = 0; j < 4; j++) ra[j] = *(const u32x4*)(pa + j * sa32 + (koff));   \
;     _Pragma("unroll") for (int j = 0; j < NB_; j++) rb[j] = *(const u32x4*)(pbv[j] + (koff));         \
;   }
; template <int NT, bool PRE> ...
;     ...
;   if (!PRE) {
;     GLOAD(ra0, rb0, 0);
;     GLOAD(ra1, rb1, 64);
;   }
;   __syncthreads();
;   for (int k0 = 0; k0 < K; k0 += 128) {
;     LSTORE(ra0, rb0, 0);
;     __syncthreads();
;     GLOAD(ra0, rb0, min(k0 + 128, K - 128));
;     __builtin_amdgcn_sched_barrier(0);
;     COMPUTE(0);
;     LSTORE(ra1, rb1, 1);
;     __syncthreads();
;     GLOAD(ra1, rb1, min(k0 + 192, K - 64));
;     __builtin_amdgcn_sched_barrier(0);
;     COMPUTE(1);
;   }
; template <int NT>
; __device__ __forceinline__ void zgemm_tile(char* ws, int m0, int n0, u16* sA, u16* sB, int tq) {
;     ...
;       int col = GEMM_COL(ni, NT * 32);
;       int cb = col & ~15;
; #pragma unroll
;       for (int mi = 0; mi < 4; mi++) {
;         int row = GEMM_ROW(mi);
;         int b = row >= NPB ? 1 : 0;
;         int n = row - b * NPB;
;         f32x4 v = acc[mi][ni];
;         if (cb < 2480) *(uint2*)(Z + (size_t)row * ZLD + col) = pack4(v);
	s_min_u32 s1, s0, 0x300
	s_lshl_b32 s54, s1, 1
	ds_read_b128 v[66:69], v64 offset:32768
	ds_read_b128 v[70:73], v64 offset:34816
	ds_read_b128 v[74:77], v64 offset:36864
	ds_read_b128 v[78:81], v64 offset:38912
	ds_read_b128 v[82:85], v86 offset:49152
	ds_read_b128 v[88:91], v65 offset:32768
	ds_read_b128 v[92:95], v65 offset:34816
	ds_read_b128 v[96:99], v65 offset:36864
	ds_read_b128 v[100:103], v65 offset:38912
	ds_read_b128 v[104:107], v87 offset:49152
	v_lshl_add_u64 v[28:29], v[58:59], 0, s[54:55]
	v_add_co_u32_e32 v30, vcc, s33, v28
	v_lshl_add_u64 v[20:21], v[56:57], 0, s[54:55]
	s_nop 0
	v_addc_co_u32_e32 v31, vcc, 0, v29, vcc
	v_add_co_u32_e32 v44, vcc, s56, v28
	s_nop 0
	s_nop 0
	v_addc_co_u32_e32 v45, vcc, 0, v29, vcc
	v_add_co_u32_e32 v46, vcc, s57, v28
	s_nop 0
	s_nop 0
	v_addc_co_u32_e32 v47, vcc, 0, v29, vcc
	s_setprio 1
	s_waitcnt lgkmcnt(5)
	v_mfma_f32_16x16x32_bf16 v[12:15], v[82:85], v[66:69], v[12:15]
	global_load_dwordx4 v[20:23], v[20:21], off offset:384
	s_nop 0
	v_mfma_f32_16x16x32_bf16 v[8:11], v[82:85], v[70:73], v[8:11]
	global_load_dwordx4 v[36:39], v[28:29], off offset:384
	s_nop 0
	v_mfma_f32_16x16x32_bf16 v[4:7], v[82:85], v[74:77], v[4:7]
	global_load_dwordx4 v[40:43], v[30:31], off offset:384
	s_nop 0
	global_load_dwordx4 v[28:31], v[44:45], off offset:384
	s_nop 0
	v_mfma_f32_16x16x32_bf16 v[0:3], v[82:85], v[78:81], v[0:3]
	global_load_dwordx4 v[44:47], v[46:47], off offset:384
	s_nop 0
	s_waitcnt lgkmcnt(0)
	v_mfma_f32_16x16x32_bf16 v[12:15], v[104:107], v[88:91], v[12:15]
	s_waitcnt vmcnt(9)
	ds_write_b128 v60, v[16:19] offset:16384
	v_mfma_f32_16x16x32_bf16 v[8:11], v[104:107], v[92:95], v[8:11]
	s_waitcnt vmcnt(8)
	ds_write_b128 v60, v[24:27]
	s_waitcnt vmcnt(7)
	ds_write_b128 v60, v[52:55] offset:4096
	v_mfma_f32_16x16x32_bf16 v[4:7], v[104:107], v[96:99], v[4:7]
	s_waitcnt vmcnt(6)
	ds_write_b128 v60, v[32:35] offset:8192
	v_mfma_f32_16x16x32_bf16 v[0:3], v[104:107], v[100:103], v[0:3]
	s_waitcnt vmcnt(5)
	ds_write_b128 v60, v[48:51] offset:12288
	s_setprio 0
	s_waitcnt lgkmcnt(0)
	s_barrier
	s_cmpk_lt_u32 s0, 0x300
	s_cbranch_scc1 .LBB0_586
	v_add_u32_e32 v86, v61, v62
	v_add_u32_e32 v87, v61, v63
	ds_read_b128 v[66:69], v64
	ds_read_b128 v[70:73], v64 offset:2048
	ds_read_b128 v[74:77], v64 offset:4096
	ds_read_b128 v[78:81], v64 offset:6144
	ds_read_b128 v[82:85], v86 offset:16384
	ds_read_b128 v[88:91], v65
	ds_read_b128 v[92:95], v65 offset:2048
	ds_read_b128 v[96:99], v65 offset:4096
	ds_read_b128 v[100:103], v65 offset:6144
	ds_read_b128 v[104:107], v87 offset:16384
	s_addk_i32 s0, 0x80
	s_setprio 1
	s_waitcnt lgkmcnt(5)
	v_mfma_f32_16x16x32_bf16 v[12:15], v[82:85], v[66:69], v[12:15]
	v_mfma_f32_16x16x32_bf16 v[8:11], v[82:85], v[70:73], v[8:11]
	v_mfma_f32_16x16x32_bf16 v[4:7], v[82:85], v[74:77], v[4:7]
	v_mfma_f32_16x16x32_bf16 v[0:3], v[82:85], v[78:81], v[0:3]
	s_waitcnt lgkmcnt(0)
	v_mfma_f32_16x16x32_bf16 v[12:15], v[104:107], v[88:91], v[12:15]
	s_waitcnt vmcnt(4)
	ds_write_b128 v60, v[20:23] offset:49152
	v_mfma_f32_16x16x32_bf16 v[8:11], v[104:107], v[92:95], v[8:11]
	s_waitcnt vmcnt(3)
	ds_write_b128 v60, v[36:39] offset:32768
	s_waitcnt vmcnt(2)
	ds_write_b128 v60, v[40:43] offset:36864
	v_mfma_f32_16x16x32_bf16 v[4:7], v[104:107], v[96:99], v[4:7]
	s_waitcnt vmcnt(1)
	ds_write_b128 v60, v[28:31] offset:40960
	v_mfma_f32_16x16x32_bf16 v[0:3], v[104:107], v[100:103], v[0:3]
	s_waitcnt vmcnt(0)
	ds_write_b128 v60, v[44:47] offset:45056
	s_setprio 0
	s_waitcnt lgkmcnt(0)
	s_barrier
	ds_read_b128 v[66:69], v64 offset:32768
	ds_read_b128 v[70:73], v64 offset:34816
	ds_read_b128 v[74:77], v64 offset:36864
	ds_read_b128 v[78:81], v64 offset:38912
	ds_read_b128 v[82:85], v86 offset:49152
	ds_read_b128 v[88:91], v65 offset:32768
	ds_read_b128 v[92:95], v65 offset:34816
	ds_read_b128 v[96:99], v65 offset:36864
	ds_read_b128 v[100:103], v65 offset:38912
	ds_read_b128 v[104:107], v87 offset:49152
	s_setprio 1
	s_waitcnt lgkmcnt(5)
	v_mfma_f32_16x16x32_bf16 v[12:15], v[82:85], v[66:69], v[12:15]
	v_mfma_f32_16x16x32_bf16 v[8:11], v[82:85], v[70:73], v[8:11]
	v_mfma_f32_16x16x32_bf16 v[4:7], v[82:85], v[74:77], v[4:7]
	v_mfma_f32_16x16x32_bf16 v[0:3], v[82:85], v[78:81], v[0:3]
	s_waitcnt lgkmcnt(0)
	v_mfma_f32_16x16x32_bf16 v[12:15], v[104:107], v[88:91], v[12:15]
	v_mfma_f32_16x16x32_bf16 v[8:11], v[104:107], v[92:95], v[8:11]
	v_mfma_f32_16x16x32_bf16 v[4:7], v[104:107], v[96:99], v[4:7]
	v_mfma_f32_16x16x32_bf16 v[0:3], v[104:107], v[100:103], v[0:3]
	s_setprio 0
	s_waitcnt lgkmcnt(0)
	s_waitcnt vmcnt(9)
	v_lshrrev_b32_e32 v16, 2, v157
	v_readlane_b32 s0, v250, 42
	v_mov_b32_e32 v19, v131
	s_nop 0
	v_and_or_b32 v16, v16, 16, s0
	v_or_b32_e32 v130, v16, v156
	v_readlane_b32 s0, v250, 37
	v_lshlrev_b32_e32 v18, 1, v130
	v_lshl_add_u64 v[18:19], s[14:15], 0, v[18:19]
	v_or_b32_e32 v17, s0, v154
	s_movk_i32 s0, 0x9b0
	v_cmp_gt_u32_e64 s[50:51], s0, v16
	s_mov_b64 s[0:1], 0x45cb800
	s_waitcnt vmcnt(4)
	v_add_u32_e32 v22, v17, v158
	v_lshl_add_u64 v[20:21], v[18:19], 0, s[0:1]
	s_and_saveexec_b64 s[0:1], s[50:51]
	s_cbranch_execz .LBB0_589
	v_cvt_pk_bf16_f32 v18, v12, v13
	v_cvt_pk_bf16_f32 v19, v14, v15
	v_mad_i64_i32 v[24:25], s[2:3], v22, s91, v[20:21]
	global_store_dwordx2 v[24:25], v[18:19], off

; #define GLOAD(ra, rb, koff)                                                        \
;   {                                                                                \
;     _Pragma("unroll") for (int j = 0; j < 4; j++) ra[j] = *(const u32x4*)(pa + j * sa32 + (koff));   \
;     _Pragma("unroll") for (int j = 0; j < NB_; j++) rb[j] = *(const u32x4*)(pbv[j] + (koff));         \
;   }
; template <int NT, bool PRE> ...
;     ...
;   const int wsw = ((tid & 7) ^ ((tid >> 4) & 7)) * 8;
;   const int rsw = (lane & 15) >> 1;
;     ...
;   if (!PRE) {
;     GLOAD(ra0, rb0, 0);
;     GLOAD(ra1, rb1, 64);
;   }
;   __syncthreads();
;   for (int k0 = 0; k0 < K; k0 += 128) {
;     LSTORE(ra0, rb0, 0);
;     __syncthreads();
;     GLOAD(ra0, rb0, min(k0 + 128, K - 128));
;     __builtin_amdgcn_sched_barrier(0);
;     COMPUTE(0);
;     LSTORE(ra1, rb1, 1);
;     __syncthreads();
;     GLOAD(ra1, rb1, min(k0 + 192, K - 64));
;     __builtin_amdgcn_sched_barrier(0);
;     COMPUTE(1);
;   }
; template <int NT>
; __device__ __forceinline__ void gemm_main(const u16* __restrict__ A, int lda, const u16* __restrict__ Bt, int ldb,
;                                           int K, int m0, int n0, f32x4 (&acc)[4][NT], u16* sA, u16* sB) {
;     ...
;   const u16* pa = A + (size_t)(m0 + (tid >> 3)) * lda + (tid & 7) * 8;
;   const u16* pbv[NT];
; #pragma unroll
;   for (int j = 0; j < NT; j++) pbv[j] = Bt + (size_t)(n0 + (tid >> 3) + 32 * j) * ldb + (tid & 7) * 8;
.LBB0_2046:
	v_readlane_b32 s2, v250, 47
	v_readlane_b32 s3, v250, 48
	s_andn2_b64 vcc, exec, s[2:3]
	s_waitcnt vmcnt(30)
	v_cndmask_b32_e64 v0, 0, 1, s[2:3]
	v_cmp_ne_u32_e64 s[46:47], 1, v0
	s_cbranch_vccnz .LBB0_2050
	s_waitcnt vmcnt(5)
	v_mov_b32_e32 v40, v169
	v_readlane_b32 s2, v250, 20
	v_lshlrev_b32_e32 v41, 4, v40
	v_and_b32_e32 v130, 0x70, v41
	v_readlane_b32 s3, v250, 21
	v_ashrrev_i32_e32 v4, 3, v40
	v_lshrrev_b32_e32 v42, 4, v40
	v_lshl_add_u64 v[0:1], s[2:3], 0, v[130:131]
	v_readlane_b32 s2, v250, 50
	v_xor_b32_e32 v43, v42, v40
	v_lshlrev_b32_e32 v43, 4, v43
	v_add_u32_e32 v2, s2, v4
	v_ashrrev_i32_e32 v3, 31, v2
	v_lshlrev_b64 v[2:3], 11, v[2:3]
	v_readlane_b32 s2, v250, 49
	v_lshl_add_u64 v[56:57], v[0:1], 0, v[2:3]
	v_and_b32_e32 v43, 0x70, v43
	v_add_u32_e32 v0, s2, v4
	v_ashrrev_i32_e32 v1, 31, v0
	v_readlane_b32 s2, v250, 18
	v_lshlrev_b64 v[0:1], 11, v[0:1]
	v_readlane_b32 s3, v250, 19
	s_waitcnt vmcnt(0)
	v_bfe_u32 v45, v40, 1, 3
	v_and_b32_e32 v44, 15, v40
	v_lshl_add_u64 v[0:1], s[2:3], 0, v[0:1]
	v_lshl_add_u64 v[58:59], v[0:1], 0, v[130:131]
	v_add_co_u32_e32 v0, vcc, s33, v58
	s_movk_i32 s2, 0xff80
	s_nop 0
	v_addc_co_u32_e32 v1, vcc, 0, v59, vcc
	v_add_co_u32_e32 v2, vcc, s56, v58
	v_and_or_b32 v60, v41, s2, v43
	s_nop 0
	v_addc_co_u32_e32 v3, vcc, 0, v59, vcc
	v_add_co_u32_e32 v4, vcc, s57, v58
	v_bfe_u32 v41, v40, 4, 2
	s_nop 0
	v_addc_co_u32_e32 v5, vcc, 0, v59, vcc
	global_load_dwordx4 v[8:11], v[58:59], off
	global_load_dwordx4 v[20:23], v[58:59], off offset:128
	global_load_dwordx4 v[36:39], v[0:1], off
	global_load_dwordx4 v[24:27], v[0:1], off offset:128
	global_load_dwordx4 v[16:19], v[2:3], off
	global_load_dwordx4 v[12:15], v[2:3], off offset:128
	global_load_dwordx4 v[32:35], v[4:5], off
	global_load_dwordx4 v[28:31], v[4:5], off offset:128
	s_nop 0
	global_load_dwordx4 v[0:3], v[56:57], off
	global_load_dwordx4 v[4:7], v[56:57], off offset:128
	v_lshlrev_b32_e32 v43, 5, v40
	v_bitop3_b32 v42, v42, v45, 3 bitop3:0x6c
	v_lshlrev_b32_e32 v40, 6, v40
	v_bitop3_b32 v41, v41, v45, 4 bitop3:0x36
	v_lshlrev_b32_e32 v62, 4, v42
	v_and_b32_e32 v40, 0xffffe000, v40
	v_lshlrev_b32_e32 v63, 4, v41
	v_lshlrev_b32_e32 v44, 7, v44
	s_movk_i32 s3, 0x800
	v_or_b32_e32 v42, v62, v40
	v_or_b32_e32 v40, v63, v40
	v_mov_b32_e32 v48, 0
	v_and_or_b32 v61, v43, s3, v44
	v_add_u32_e32 v64, v42, v44
	v_add_u32_e32 v65, v40, v44
	v_mov_b32_e32 v49, v48
	v_mov_b32_e32 v50, v48
	v_mov_b32_e32 v51, v48
	v_mov_b32_e32 v52, v48
	v_mov_b32_e32 v53, v48
	v_mov_b32_e32 v54, v48
	v_mov_b32_e32 v55, v48
	v_mov_b32_e32 v44, v48
	v_mov_b32_e32 v45, v48
	v_mov_b32_e32 v46, v48
	v_mov_b32_e32 v47, v48
	v_mov_b32_e32 v40, v48
	v_mov_b32_e32 v41, v48
	v_mov_b32_e32 v42, v48
	v_mov_b32_e32 v43, v48
	s_barrier
	s_waitcnt vmcnt(8)
	ds_write_b128 v60, v[8:11]
	s_waitcnt vmcnt(7)
	ds_write_b128 v60, v[36:39] offset:4096
	s_waitcnt vmcnt(5)
	ds_write_b128 v60, v[16:19] offset:8192
	s_waitcnt vmcnt(3)
	ds_write_b128 v60, v[32:35] offset:12288
	s_waitcnt vmcnt(1)
	ds_write_b128 v60, v[0:3] offset:16384
	s_waitcnt vmcnt(0)
	s_waitcnt lgkmcnt(0)
	s_barrier
.LBB0_2048:
	s_add_i32 s3, s2, 0x100
	s_min_u32 s3, s3, 0x380
	s_lshl_b32 s54, s3, 1
	v_add_u32_e32 v86, v61, v62
	v_add_u32_e32 v87, v61, v63
	ds_read_b128 v[66:69], v64
	ds_read_b128 v[70:73], v64 offset:2048
	ds_read_b128 v[74:77], v64 offset:4096
	ds_read_b128 v[78:81], v64 offset:6144
	ds_read_b128 v[82:85], v86 offset:16384
	ds_read_b128 v[88:91], v65
	ds_read_b128 v[92:95], v65 offset:2048
	ds_read_b128 v[96:99], v65 offset:4096
	ds_read_b128 v[100:103], v65 offset:6144
	ds_read_b128 v[104:107], v87 offset:16384
	v_lshl_add_u64 v[8:9], v[58:59], 0, s[54:55]
	v_add_co_u32_e32 v16, vcc, s33, v8
	v_lshl_add_u64 v[0:1], v[56:57], 0, s[54:55]
	s_nop 0
	v_addc_co_u32_e32 v17, vcc, 0, v9, vcc
	v_add_co_u32_e32 v18, vcc, s56, v8
	s_nop 0
	s_nop 0
	v_addc_co_u32_e32 v19, vcc, 0, v9, vcc
	v_add_co_u32_e32 v32, vcc, s57, v8
	s_nop 0
	s_nop 0
	v_addc_co_u32_e32 v33, vcc, 0, v9, vcc
	s_addk_i32 s2, 0x80
	s_setprio 1
	s_waitcnt lgkmcnt(5)
	v_mfma_f32_16x16x32_bf16 v[48:51], v[82:85], v[66:69], v[48:51]
	global_load_dwordx4 v[0:3], v[0:1], off
	s_nop 0
	v_mfma_f32_16x16x32_bf16 v[52:55], v[82:85], v[70:73], v[52:55]
	global_load_dwordx4 v[8:11], v[8:9], off
	s_nop 0
	v_mfma_f32_16x16x32_bf16 v[44:47], v[82:85], v[74:77], v[44:47]
	global_load_dwordx4 v[36:39], v[16:17], off
	s_nop 0
	global_load_dwordx4 v[16:19], v[18:19], off
	s_nop 0
	v_mfma_f32_16x16x32_bf16 v[40:43], v[82:85], v[78:81], v[40:43]
	global_load_dwordx4 v[32:35], v[32:33], off
	s_nop 0
	s_waitcnt lgkmcnt(0)
	v_mfma_f32_16x16x32_bf16 v[48:51], v[104:107], v[88:91], v[48:51]
	s_waitcnt vmcnt(9)
	ds_write_b128 v60, v[4:7] offset:49152
	v_mfma_f32_16x16x32_bf16 v[52:55], v[104:107], v[92:95], v[52:55]
	s_waitcnt vmcnt(8)
	ds_write_b128 v60, v[20:23] offset:32768
	s_waitcnt vmcnt(7)
	ds_write_b128 v60, v[24:27] offset:36864
	v_mfma_f32_16x16x32_bf16 v[44:47], v[104:107], v[96:99], v[44:47]
	s_waitcnt vmcnt(6)
	ds_write_b128 v60, v[12:15] offset:40960
	v_mfma_f32_16x16x32_bf16 v[40:43], v[104:107], v[100:103], v[40:43]
	s_waitcnt vmcnt(5)
	ds_write_b128 v60, v[28:31] offset:45056
	s_setprio 0
	s_waitcnt lgkmcnt(0)
	s_barrier
; #define GLOAD(ra, rb, koff)                                                        \
;   {                                                                                \
;     _Pragma("unroll") for (int j = 0; j < 4; j++) ra[j] = *(const u32x4*)(pa + j * sa32 + (koff));   \
;     _Pragma("unroll") for (int j = 0; j < NB_; j++) rb[j] = *(const u32x4*)(pbv[j] + (koff));         \
;   }
; template <int NT, bool PRE> ...
;     ...
;   if (!PRE) {
;     GLOAD(ra0, rb0, 0);
;     GLOAD(ra1, rb1, 64);
;   }
;   __syncthreads();
;   for (int k0 = 0; k0 < K; k0 += 128) {
;     LSTORE(ra0, rb0, 0);
;     __syncthreads();
;     GLOAD(ra0, rb0, min(k0 + 128, K - 128));
;     __builtin_amdgcn_sched_barrier(0);
;     COMPUTE(0);
;     LSTORE(ra1, rb1, 1);
;     __syncthreads();
;     GLOAD(ra1, rb1, min(k0 + 192, K - 64));
;     __builtin_amdgcn_sched_barrier(0);
;     COMPUTE(1);
;   }
; template <int EPI, int NT>
; __device__ __forceinline__ void gemm_tile_plain(char* ws, const u16* A, int lda, const u16* Bt, int K, int m0, int n0,
;                                                 u16* sA, u16* sB, int tq) {
;     ...
; #pragma unroll
;   for (int ni = 0; ni < NT; ni++) {
;     int col = GEMM_COL(ni, NT * 32);
; #pragma unroll
;     for (int mi = 0; mi < 4; mi++) {
;       int row = GEMM_ROW(mi);
;       f32x4 v = acc[mi][ni];
;       if (EPI == 0) {
;         *(float4*)((float*)(ws + O_F32) + (size_t)row * 1024 + col) = make_float4(v[0], v[1], v[2], v[3]);
	s_min_u32 s3, s2, 0x300
	s_lshl_b32 s54, s3, 1
	ds_read_b128 v[66:69], v64 offset:32768
	ds_read_b128 v[70:73], v64 offset:34816
	ds_read_b128 v[74:77], v64 offset:36864
	ds_read_b128 v[78:81], v64 offset:38912
	ds_read_b128 v[82:85], v86 offset:49152
	ds_read_b128 v[88:91], v65 offset:32768
	ds_read_b128 v[92:95], v65 offset:34816
	ds_read_b128 v[96:99], v65 offset:36864
	ds_read_b128 v[100:103], v65 offset:38912
	ds_read_b128 v[104:107], v87 offset:49152
	v_lshl_add_u64 v[12:13], v[58:59], 0, s[54:55]
	v_add_co_u32_e32 v14, vcc, s33, v12
	v_lshl_add_u64 v[4:5], v[56:57], 0, s[54:55]
	s_nop 0
	v_addc_co_u32_e32 v15, vcc, 0, v13, vcc
	v_add_co_u32_e32 v28, vcc, s56, v12
	s_nop 0
	s_nop 0
	v_addc_co_u32_e32 v29, vcc, 0, v13, vcc
	v_add_co_u32_e32 v30, vcc, s57, v12
	s_nop 0
	s_nop 0
	v_addc_co_u32_e32 v31, vcc, 0, v13, vcc
	s_setprio 1
	s_waitcnt lgkmcnt(5)
	v_mfma_f32_16x16x32_bf16 v[48:51], v[82:85], v[66:69], v[48:51]
	global_load_dwordx4 v[4:7], v[4:5], off offset:384
	s_nop 0
	v_mfma_f32_16x16x32_bf16 v[52:55], v[82:85], v[70:73], v[52:55]
	global_load_dwordx4 v[20:23], v[12:13], off offset:384
	s_nop 0
	v_mfma_f32_16x16x32_bf16 v[44:47], v[82:85], v[74:77], v[44:47]
	global_load_dwordx4 v[24:27], v[14:15], off offset:384
	s_nop 0
	global_load_dwordx4 v[12:15], v[28:29], off offset:384
	s_nop 0
	v_mfma_f32_16x16x32_bf16 v[40:43], v[82:85], v[78:81], v[40:43]
	global_load_dwordx4 v[28:31], v[30:31], off offset:384
	s_nop 0
	s_waitcnt lgkmcnt(0)
	v_mfma_f32_16x16x32_bf16 v[48:51], v[104:107], v[88:91], v[48:51]
	s_waitcnt vmcnt(9)
	ds_write_b128 v60, v[0:3] offset:16384
	v_mfma_f32_16x16x32_bf16 v[52:55], v[104:107], v[92:95], v[52:55]
	s_waitcnt vmcnt(8)
	ds_write_b128 v60, v[8:11]
	s_waitcnt vmcnt(7)
	ds_write_b128 v60, v[36:39] offset:4096
	v_mfma_f32_16x16x32_bf16 v[44:47], v[104:107], v[96:99], v[44:47]
	s_waitcnt vmcnt(6)
	ds_write_b128 v60, v[16:19] offset:8192
	v_mfma_f32_16x16x32_bf16 v[40:43], v[104:107], v[100:103], v[40:43]
	s_waitcnt vmcnt(5)
	ds_write_b128 v60, v[32:35] offset:12288
	s_setprio 0
	s_waitcnt lgkmcnt(0)
	s_barrier
	s_cmpk_lt_u32 s2, 0x300
	s_cbranch_scc1 .LBB0_2048
	v_add_u32_e32 v86, v61, v62
	v_add_u32_e32 v87, v61, v63
	ds_read_b128 v[66:69], v64
	ds_read_b128 v[70:73], v64 offset:2048
	ds_read_b128 v[74:77], v64 offset:4096
	ds_read_b128 v[78:81], v64 offset:6144
	ds_read_b128 v[82:85], v86 offset:16384
	ds_read_b128 v[88:91], v65
	ds_read_b128 v[92:95], v65 offset:2048
	ds_read_b128 v[96:99], v65 offset:4096
	ds_read_b128 v[100:103], v65 offset:6144
	ds_read_b128 v[104:107], v87 offset:16384
	s_addk_i32 s2, 0x80
	s_setprio 1
	s_waitcnt lgkmcnt(5)
	v_mfma_f32_16x16x32_bf16 v[48:51], v[82:85], v[66:69], v[48:51]
	v_mfma_f32_16x16x32_bf16 v[52:55], v[82:85], v[70:73], v[52:55]
	v_mfma_f32_16x16x32_bf16 v[44:47], v[82:85], v[74:77], v[44:47]
	v_mfma_f32_16x16x32_bf16 v[40:43], v[82:85], v[78:81], v[40:43]
	s_waitcnt lgkmcnt(0)
	v_mfma_f32_16x16x32_bf16 v[48:51], v[104:107], v[88:91], v[48:51]
	s_waitcnt vmcnt(4)
	ds_write_b128 v60, v[4:7] offset:49152
	v_mfma_f32_16x16x32_bf16 v[52:55], v[104:107], v[92:95], v[52:55]
	s_waitcnt vmcnt(3)
	ds_write_b128 v60, v[20:23] offset:32768
	s_waitcnt vmcnt(2)
	ds_write_b128 v60, v[24:27] offset:36864
	v_mfma_f32_16x16x32_bf16 v[44:47], v[104:107], v[96:99], v[44:47]
	s_waitcnt vmcnt(1)
	ds_write_b128 v60, v[12:15] offset:40960
	v_mfma_f32_16x16x32_bf16 v[40:43], v[104:107], v[100:103], v[40:43]
	s_waitcnt vmcnt(0)
	ds_write_b128 v60, v[28:31] offset:45056
	s_setprio 0
	s_waitcnt lgkmcnt(0)
	s_barrier
	ds_read_b128 v[66:69], v64 offset:32768
	ds_read_b128 v[70:73], v64 offset:34816
	ds_read_b128 v[74:77], v64 offset:36864
	ds_read_b128 v[78:81], v64 offset:38912
	ds_read_b128 v[82:85], v86 offset:49152
	ds_read_b128 v[88:91], v65 offset:32768
	ds_read_b128 v[92:95], v65 offset:34816
	ds_read_b128 v[96:99], v65 offset:36864
	ds_read_b128 v[100:103], v65 offset:38912
	ds_read_b128 v[104:107], v87 offset:49152
	s_setprio 1
	s_waitcnt lgkmcnt(5)
	v_mfma_f32_16x16x32_bf16 v[48:51], v[82:85], v[66:69], v[48:51]
	v_mfma_f32_16x16x32_bf16 v[52:55], v[82:85], v[70:73], v[52:55]
	v_mfma_f32_16x16x32_bf16 v[44:47], v[82:85], v[74:77], v[44:47]
	v_mfma_f32_16x16x32_bf16 v[40:43], v[82:85], v[78:81], v[40:43]
	s_waitcnt lgkmcnt(0)
	v_mfma_f32_16x16x32_bf16 v[48:51], v[104:107], v[88:91], v[48:51]
	v_mfma_f32_16x16x32_bf16 v[52:55], v[104:107], v[92:95], v[52:55]
	v_mfma_f32_16x16x32_bf16 v[44:47], v[104:107], v[96:99], v[44:47]
	v_mfma_f32_16x16x32_bf16 v[40:43], v[104:107], v[100:103], v[40:43]
	s_setprio 0
	s_waitcnt lgkmcnt(0)
	v_readlane_b32 s2, v250, 50
	s_waitcnt vmcnt(9)
	v_and_b32_e32 v0, 0xffffffc0, v148
	v_and_or_b32 v130, v147, 28, s2
	v_readlane_b32 s2, v250, 49
	v_lshl_add_u64 v[2:3], v[130:131], 2, s[0:1]
	s_mov_b64 s[0:1], 0xcb4b800
	v_and_or_b32 v1, v146, 15, s2
	v_add_u32_e32 v0, v1, v0
	v_ashrrev_i32_e32 v1, 31, v0
	v_lshl_add_u64 v[2:3], v[2:3], 0, s[0:1]
	s_waitcnt vmcnt(4)
	v_lshlrev_b64 v[4:5], 12, v[0:1]
	v_lshl_add_u64 v[4:5], v[2:3], 0, v[4:5]
	global_store_dwordx4 v[4:5], v[48:51], off
	v_or_b32_e32 v4, 16, v0
	v_ashrrev_i32_e32 v5, 31, v4
	v_lshlrev_b64 v[4:5], 12, v[4:5]
	v_lshl_add_u64 v[4:5], v[2:3], 0, v[4:5]
	global_store_dwordx4 v[4:5], v[52:55], off
	v_or_b32_e32 v4, 32, v0
	v_or_b32_e32 v0, 48, v0
	v_ashrrev_i32_e32 v5, 31, v4
	v_ashrrev_i32_e32 v1, 31, v0
	v_lshlrev_b64 v[4:5], 12, v[4:5]
	v_lshlrev_b64 v[0:1], 12, v[0:1]
	v_lshl_add_u64 v[4:5], v[2:3], 0, v[4:5]
	v_lshl_add_u64 v[0:1], v[2:3], 0, v[0:1]
	global_store_dwordx4 v[4:5], v[44:47], off
	global_store_dwordx4 v[0:1], v[40:43], off

; #define GLOAD(ra, rb, koff)                                                        \
;   {                                                                                \
;     _Pragma("unroll") for (int j = 0; j < 4; j++) ra[j] = *(const u32x4*)(pa + j * sa32 + (koff));   \
;     _Pragma("unroll") for (int j = 0; j < NB_; j++) rb[j] = *(const u32x4*)(pbv[j] + (koff));         \
;   }
; template <int NT, bool PRE> ...
;     ...
;   const int wsw = ((tid & 7) ^ ((tid >> 4) & 7)) * 8;
;   const int rsw = (lane & 15) >> 1;
;     ...
;   if (!PRE) {
;     GLOAD(ra0, rb0, 0);
;     GLOAD(ra1, rb1, 64);
;   }
;   __syncthreads();
;   for (int k0 = 0; k0 < K; k0 += 128) {
;     LSTORE(ra0, rb0, 0);
;     __syncthreads();
;     GLOAD(ra0, rb0, min(k0 + 128, K - 128));
;     __builtin_amdgcn_sched_barrier(0);
;     COMPUTE(0);
;     LSTORE(ra1, rb1, 1);
;     __syncthreads();
;     GLOAD(ra1, rb1, min(k0 + 192, K - 64));
;     __builtin_amdgcn_sched_barrier(0);
;     COMPUTE(1);
;   }
; template <int NT>
; __device__ __forceinline__ void gemm_main(const u16* __restrict__ A, int lda, const u16* __restrict__ Bt, int ldb,
;                                           int K, int m0, int n0, f32x4 (&acc)[4][NT], u16* sA, u16* sB) {
;     ...
;   const u16* pa = A + (size_t)(m0 + (tid >> 3)) * lda + (tid & 7) * 8;
;   const u16* pbv[NT];
; #pragma unroll
;   for (int j = 0; j < NT; j++) pbv[j] = Bt + (size_t)(n0 + (tid >> 3) + 32 * j) * ldb + (tid & 7) * 8;
.LBB0_2233:
	v_readlane_b32 s2, v250, 53
	v_readlane_b32 s3, v250, 54
	s_andn2_b64 vcc, exec, s[2:3]
	s_cbranch_vccnz .LBB0_2237
	s_waitcnt vmcnt(17)
	v_mov_b32_e32 v40, v169
	v_readlane_b32 s2, v250, 26
	v_lshlrev_b32_e32 v41, 4, v40
	v_and_b32_e32 v130, 0x70, v41
	v_readlane_b32 s3, v250, 27
	v_ashrrev_i32_e32 v4, 3, v40
	v_lshrrev_b32_e32 v42, 4, v40
	v_lshl_add_u64 v[0:1], s[2:3], 0, v[130:131]
	v_readlane_b32 s2, v250, 56
	v_xor_b32_e32 v43, v42, v40
	v_lshlrev_b32_e32 v43, 4, v43
	v_add_u32_e32 v2, s2, v4
	v_ashrrev_i32_e32 v3, 31, v2
	v_lshlrev_b64 v[2:3], 11, v[2:3]
	v_readlane_b32 s2, v250, 55
	s_waitcnt vmcnt(16)
	v_lshl_add_u64 v[56:57], v[0:1], 0, v[2:3]
	v_and_b32_e32 v43, 0x70, v43
	v_add_u32_e32 v0, s2, v4
	v_ashrrev_i32_e32 v1, 31, v0
	v_readlane_b32 s2, v250, 24
	v_lshlrev_b64 v[0:1], 11, v[0:1]
	v_readlane_b32 s3, v250, 25
	v_bfe_u32 v45, v40, 1, 3
	v_and_b32_e32 v44, 15, v40
	v_lshl_add_u64 v[0:1], s[2:3], 0, v[0:1]
	v_lshl_add_u64 v[58:59], v[0:1], 0, v[130:131]
	v_add_co_u32_e32 v0, vcc, s33, v58
	s_movk_i32 s2, 0xff80
	s_nop 0
	v_addc_co_u32_e32 v1, vcc, 0, v59, vcc
	v_add_co_u32_e32 v2, vcc, s56, v58
	v_and_or_b32 v60, v41, s2, v43
	s_nop 0
	v_addc_co_u32_e32 v3, vcc, 0, v59, vcc
	v_add_co_u32_e32 v4, vcc, s57, v58
	v_bfe_u32 v41, v40, 4, 2
	s_nop 0
	v_addc_co_u32_e32 v5, vcc, 0, v59, vcc
	global_load_dwordx4 v[8:11], v[58:59], off
	global_load_dwordx4 v[20:23], v[58:59], off offset:128
	global_load_dwordx4 v[36:39], v[0:1], off
	global_load_dwordx4 v[24:27], v[0:1], off offset:128
	global_load_dwordx4 v[16:19], v[2:3], off
	global_load_dwordx4 v[12:15], v[2:3], off offset:128
	global_load_dwordx4 v[32:35], v[4:5], off
	global_load_dwordx4 v[28:31], v[4:5], off offset:128
	s_nop 0
	global_load_dwordx4 v[0:3], v[56:57], off
	global_load_dwordx4 v[4:7], v[56:57], off offset:128
	v_lshlrev_b32_e32 v43, 5, v40
	v_bitop3_b32 v42, v42, v45, 3 bitop3:0x6c
	v_lshlrev_b32_e32 v40, 6, v40
	v_bitop3_b32 v41, v41, v45, 4 bitop3:0x36
	v_lshlrev_b32_e32 v62, 4, v42
	v_and_b32_e32 v40, 0xffffe000, v40
	v_lshlrev_b32_e32 v63, 4, v41
	v_lshlrev_b32_e32 v44, 7, v44
	s_movk_i32 s3, 0x800
	v_or_b32_e32 v42, v62, v40
	v_or_b32_e32 v40, v63, v40
	v_mov_b32_e32 v52, 0
	v_and_or_b32 v61, v43, s3, v44
	v_add_u32_e32 v64, v42, v44
	v_add_u32_e32 v65, v40, v44
	v_mov_b32_e32 v53, v52
	v_mov_b32_e32 v54, v52
	v_mov_b32_e32 v55, v52
	v_mov_b32_e32 v48, v52
	v_mov_b32_e32 v49, v52
	v_mov_b32_e32 v50, v52
	v_mov_b32_e32 v51, v52
	v_mov_b32_e32 v44, v52
	v_mov_b32_e32 v45, v52
	v_mov_b32_e32 v46, v52
	v_mov_b32_e32 v47, v52
	v_mov_b32_e32 v40, v52
	v_mov_b32_e32 v41, v52
	v_mov_b32_e32 v42, v52
	v_mov_b32_e32 v43, v52
	s_barrier
	s_waitcnt vmcnt(8)
	ds_write_b128 v60, v[8:11]
	s_waitcnt vmcnt(7)
	ds_write_b128 v60, v[36:39] offset:4096
	s_waitcnt vmcnt(5)
	ds_write_b128 v60, v[16:19] offset:8192
	s_waitcnt vmcnt(3)
	ds_write_b128 v60, v[32:35] offset:12288
	s_waitcnt vmcnt(1)
	ds_write_b128 v60, v[0:3] offset:16384
	s_waitcnt vmcnt(0)
	s_waitcnt lgkmcnt(0)
	s_barrier
.LBB0_2235:
	s_add_i32 s3, s2, 0x100
	s_min_u32 s3, s3, 0x380
	s_lshl_b32 s54, s3, 1
	v_add_u32_e32 v86, v61, v62
	v_add_u32_e32 v87, v61, v63
	ds_read_b128 v[66:69], v64
	ds_read_b128 v[70:73], v64 offset:2048
	ds_read_b128 v[74:77], v64 offset:4096
	ds_read_b128 v[78:81], v64 offset:6144
	ds_read_b128 v[82:85], v86 offset:16384
	ds_read_b128 v[88:91], v65
	ds_read_b128 v[92:95], v65 offset:2048
	ds_read_b128 v[96:99], v65 offset:4096
	ds_read_b128 v[100:103], v65 offset:6144
	ds_read_b128 v[104:107], v87 offset:16384
	v_lshl_add_u64 v[8:9], v[58:59], 0, s[54:55]
	v_add_co_u32_e32 v16, vcc, s33, v8
	v_lshl_add_u64 v[0:1], v[56:57], 0, s[54:55]
	s_nop 0
	v_addc_co_u32_e32 v17, vcc, 0, v9, vcc
	v_add_co_u32_e32 v18, vcc, s56, v8
	s_nop 0
	s_nop 0
	v_addc_co_u32_e32 v19, vcc, 0, v9, vcc
	v_add_co_u32_e32 v32, vcc, s57, v8
	s_nop 0
	s_nop 0
	v_addc_co_u32_e32 v33, vcc, 0, v9, vcc
	s_addk_i32 s2, 0x80
	s_setprio 1
	s_waitcnt lgkmcnt(5)
	v_mfma_f32_16x16x32_bf16 v[52:55], v[82:85], v[66:69], v[52:55]
	global_load_dwordx4 v[0:3], v[0:1], off
	s_nop 0
	v_mfma_f32_16x16x32_bf16 v[48:51], v[82:85], v[70:73], v[48:51]
	global_load_dwordx4 v[8:11], v[8:9], off
	s_nop 0
	v_mfma_f32_16x16x32_bf16 v[44:47], v[82:85], v[74:77], v[44:47]
	global_load_dwordx4 v[36:39], v[16:17], off
	s_nop 0
	global_load_dwordx4 v[16:19], v[18:19], off
	s_nop 0
	v_mfma_f32_16x16x32_bf16 v[40:43], v[82:85], v[78:81], v[40:43]
	global_load_dwordx4 v[32:35], v[32:33], off
	s_nop 0
	s_waitcnt lgkmcnt(0)
	v_mfma_f32_16x16x32_bf16 v[52:55], v[104:107], v[88:91], v[52:55]
	s_waitcnt vmcnt(9)
	ds_write_b128 v60, v[4:7] offset:49152
	v_mfma_f32_16x16x32_bf16 v[48:51], v[104:107], v[92:95], v[48:51]
	s_waitcnt vmcnt(8)
	ds_write_b128 v60, v[20:23] offset:32768
	s_waitcnt vmcnt(7)
	ds_write_b128 v60, v[24:27] offset:36864
	v_mfma_f32_16x16x32_bf16 v[44:47], v[104:107], v[96:99], v[44:47]
	s_waitcnt vmcnt(6)
	ds_write_b128 v60, v[12:15] offset:40960
	v_mfma_f32_16x16x32_bf16 v[40:43], v[104:107], v[100:103], v[40:43]
	s_waitcnt vmcnt(5)
	ds_write_b128 v60, v[28:31] offset:45056
	s_setprio 0
	s_waitcnt lgkmcnt(0)
	s_barrier
; #define GLOAD(ra, rb, koff)                                                        \
;   {                                                                                \
;     _Pragma("unroll") for (int j = 0; j < 4; j++) ra[j] = *(const u32x4*)(pa + j * sa32 + (koff));   \
;     _Pragma("unroll") for (int j = 0; j < NB_; j++) rb[j] = *(const u32x4*)(pbv[j] + (koff));         \
;   }
; template <int NT, bool PRE> ...
;     ...
;   if (!PRE) {
;     GLOAD(ra0, rb0, 0);
;     GLOAD(ra1, rb1, 64);
;   }
;   __syncthreads();
;   for (int k0 = 0; k0 < K; k0 += 128) {
;     LSTORE(ra0, rb0, 0);
;     __syncthreads();
;     GLOAD(ra0, rb0, min(k0 + 128, K - 128));
;     __builtin_amdgcn_sched_barrier(0);
;     COMPUTE(0);
;     LSTORE(ra1, rb1, 1);
;     __syncthreads();
;     GLOAD(ra1, rb1, min(k0 + 192, K - 64));
;     __builtin_amdgcn_sched_barrier(0);
;     COMPUTE(1);
;   }
; template <int EPI, int NT>
; __device__ __forceinline__ void gemm_tile_plain(char* ws, const u16* A, int lda, const u16* Bt, int K, int m0, int n0,
;                                                 u16* sA, u16* sB, int tq) {
;     ...
; #pragma unroll
;   for (int ni = 0; ni < NT; ni++) {
;     int col = GEMM_COL(ni, NT * 32);
; #pragma unroll
;     for (int mi = 0; mi < 4; mi++) {
;       int row = GEMM_ROW(mi);
;       f32x4 v = acc[mi][ni];
;       if (EPI == 0) {
;         *(float4*)((float*)(ws + O_F32) + (size_t)row * 1024 + col) = make_float4(v[0], v[1], v[2], v[3]);
;       } else {
;         f32x4 o;
; #pragma unroll
;         for (int r = 0; r < 4; r++) {
;           float x = fmaxf(v[r], 0.f);
;           o[r] = x * x;
;         }
;         *(uint2*)((u16*)(ws + O_HID) + (size_t)row * 4096 + col) = pack4(o);
	s_min_u32 s3, s2, 0x300
	s_lshl_b32 s54, s3, 1
	ds_read_b128 v[66:69], v64 offset:32768
	ds_read_b128 v[70:73], v64 offset:34816
	ds_read_b128 v[74:77], v64 offset:36864
	ds_read_b128 v[78:81], v64 offset:38912
	ds_read_b128 v[82:85], v86 offset:49152
	ds_read_b128 v[88:91], v65 offset:32768
	ds_read_b128 v[92:95], v65 offset:34816
	ds_read_b128 v[96:99], v65 offset:36864
	ds_read_b128 v[100:103], v65 offset:38912
	ds_read_b128 v[104:107], v87 offset:49152
	v_lshl_add_u64 v[12:13], v[58:59], 0, s[54:55]
	v_add_co_u32_e32 v14, vcc, s33, v12
	v_lshl_add_u64 v[4:5], v[56:57], 0, s[54:55]
	s_nop 0
	v_addc_co_u32_e32 v15, vcc, 0, v13, vcc
	v_add_co_u32_e32 v28, vcc, s56, v12
	s_nop 0
	s_nop 0
	v_addc_co_u32_e32 v29, vcc, 0, v13, vcc
	v_add_co_u32_e32 v30, vcc, s57, v12
	s_nop 0
	s_nop 0
	v_addc_co_u32_e32 v31, vcc, 0, v13, vcc
	s_setprio 1
	s_waitcnt lgkmcnt(5)
	v_mfma_f32_16x16x32_bf16 v[52:55], v[82:85], v[66:69], v[52:55]
	global_load_dwordx4 v[4:7], v[4:5], off offset:384
	s_nop 0
	v_mfma_f32_16x16x32_bf16 v[48:51], v[82:85], v[70:73], v[48:51]
	global_load_dwordx4 v[20:23], v[12:13], off offset:384
	s_nop 0
	v_mfma_f32_16x16x32_bf16 v[44:47], v[82:85], v[74:77], v[44:47]
	global_load_dwordx4 v[24:27], v[14:15], off offset:384
	s_nop 0
	global_load_dwordx4 v[12:15], v[28:29], off offset:384
	s_nop 0
	v_mfma_f32_16x16x32_bf16 v[40:43], v[82:85], v[78:81], v[40:43]
	global_load_dwordx4 v[28:31], v[30:31], off offset:384
	s_nop 0
	s_waitcnt lgkmcnt(0)
	v_mfma_f32_16x16x32_bf16 v[52:55], v[104:107], v[88:91], v[52:55]
	s_waitcnt vmcnt(9)
	ds_write_b128 v60, v[0:3] offset:16384
	v_mfma_f32_16x16x32_bf16 v[48:51], v[104:107], v[92:95], v[48:51]
	s_waitcnt vmcnt(8)
	ds_write_b128 v60, v[8:11]
	s_waitcnt vmcnt(7)
	ds_write_b128 v60, v[36:39] offset:4096
	v_mfma_f32_16x16x32_bf16 v[44:47], v[104:107], v[96:99], v[44:47]
	s_waitcnt vmcnt(6)
	ds_write_b128 v60, v[16:19] offset:8192
	v_mfma_f32_16x16x32_bf16 v[40:43], v[104:107], v[100:103], v[40:43]
	s_waitcnt vmcnt(5)
	ds_write_b128 v60, v[32:35] offset:12288
	s_setprio 0
	s_waitcnt lgkmcnt(0)
	s_barrier
	s_cmpk_lt_u32 s2, 0x300
	s_cbranch_scc1 .LBB0_2235
	v_add_u32_e32 v86, v61, v62
	v_add_u32_e32 v87, v61, v63
	ds_read_b128 v[66:69], v64
	ds_read_b128 v[70:73], v64 offset:2048
	ds_read_b128 v[74:77], v64 offset:4096
	ds_read_b128 v[78:81], v64 offset:6144
	ds_read_b128 v[82:85], v86 offset:16384
	ds_read_b128 v[88:91], v65
	ds_read_b128 v[92:95], v65 offset:2048
	ds_read_b128 v[96:99], v65 offset:4096
	ds_read_b128 v[100:103], v65 offset:6144
	ds_read_b128 v[104:107], v87 offset:16384
	s_addk_i32 s2, 0x80
	s_setprio 1
	s_waitcnt lgkmcnt(5)
	v_mfma_f32_16x16x32_bf16 v[52:55], v[82:85], v[66:69], v[52:55]
	v_mfma_f32_16x16x32_bf16 v[48:51], v[82:85], v[70:73], v[48:51]
	v_mfma_f32_16x16x32_bf16 v[44:47], v[82:85], v[74:77], v[44:47]
	v_mfma_f32_16x16x32_bf16 v[40:43], v[82:85], v[78:81], v[40:43]
	s_waitcnt lgkmcnt(0)
	v_mfma_f32_16x16x32_bf16 v[52:55], v[104:107], v[88:91], v[52:55]
	s_waitcnt vmcnt(4)
	ds_write_b128 v60, v[4:7] offset:49152
	v_mfma_f32_16x16x32_bf16 v[48:51], v[104:107], v[92:95], v[48:51]
	s_waitcnt vmcnt(3)
	ds_write_b128 v60, v[20:23] offset:32768
	s_waitcnt vmcnt(2)
	ds_write_b128 v60, v[24:27] offset:36864
	v_mfma_f32_16x16x32_bf16 v[44:47], v[104:107], v[96:99], v[44:47]
	s_waitcnt vmcnt(1)
	ds_write_b128 v60, v[12:15] offset:40960
	v_mfma_f32_16x16x32_bf16 v[40:43], v[104:107], v[100:103], v[40:43]
	s_waitcnt vmcnt(0)
	ds_write_b128 v60, v[28:31] offset:45056
	s_setprio 0
	s_waitcnt lgkmcnt(0)
	s_barrier
	ds_read_b128 v[66:69], v64 offset:32768
	ds_read_b128 v[70:73], v64 offset:34816
	ds_read_b128 v[74:77], v64 offset:36864
	ds_read_b128 v[78:81], v64 offset:38912
	ds_read_b128 v[82:85], v86 offset:49152
	ds_read_b128 v[88:91], v65 offset:32768
	ds_read_b128 v[92:95], v65 offset:34816
	ds_read_b128 v[96:99], v65 offset:36864
	ds_read_b128 v[100:103], v65 offset:38912
	ds_read_b128 v[104:107], v87 offset:49152
	s_setprio 1
	s_waitcnt lgkmcnt(5)
	v_mfma_f32_16x16x32_bf16 v[52:55], v[82:85], v[66:69], v[52:55]
	v_mfma_f32_16x16x32_bf16 v[48:51], v[82:85], v[70:73], v[48:51]
	v_mfma_f32_16x16x32_bf16 v[44:47], v[82:85], v[74:77], v[44:47]
	v_mfma_f32_16x16x32_bf16 v[40:43], v[82:85], v[78:81], v[40:43]
	s_waitcnt lgkmcnt(0)
	v_mfma_f32_16x16x32_bf16 v[52:55], v[104:107], v[88:91], v[52:55]
	v_mfma_f32_16x16x32_bf16 v[48:51], v[104:107], v[92:95], v[48:51]
	v_mfma_f32_16x16x32_bf16 v[44:47], v[104:107], v[96:99], v[44:47]
	v_mfma_f32_16x16x32_bf16 v[40:43], v[104:107], v[100:103], v[40:43]
	s_setprio 0
	s_waitcnt lgkmcnt(0)
	v_readlane_b32 s2, v250, 56
	s_waitcnt vmcnt(9)
	v_and_b32_e32 v0, 0xffffffc0, v148
	v_and_or_b32 v1, v147, 28, s2
	v_lshlrev_b32_e32 v130, 1, v1
	v_max_f32_e32 v1, v52, v52
	s_waitcnt vmcnt(4)
	v_max_f32_e32 v4, 0, v1
	v_max_f32_e32 v1, v53, v53
	v_readlane_b32 s2, v250, 55
	v_max_f32_e32 v5, 0, v1
	v_max_f32_e32 v1, v54, v54
	v_and_or_b32 v2, v146, 15, s2
	v_max_f32_e32 v6, 0, v1
	v_max_f32_e32 v1, v55, v55
	v_add_u32_e32 v0, v2, v0
	v_max_f32_e32 v7, 0, v1
	v_lshl_add_u64 v[2:3], s[0:1], 0, v[130:131]
	s_mov_b64 s[0:1], 0x45cb800
	v_pk_mul_f32 v[4:5], v[4:5], v[4:5]
	v_pk_mul_f32 v[6:7], v[6:7], v[6:7]
	v_ashrrev_i32_e32 v1, 31, v0
	v_lshl_add_u64 v[2:3], v[2:3], 0, s[0:1]
	v_cvt_pk_bf16_f32 v4, v4, v5
	v_cvt_pk_bf16_f32 v5, v6, v7
	v_lshlrev_b64 v[6:7], 13, v[0:1]
	v_lshl_add_u64 v[6:7], v[2:3], 0, v[6:7]
	v_max_f32_e32 v1, v48, v48
	global_store_dwordx2 v[6:7], v[4:5], off
	v_max_f32_e32 v4, 0, v1
	v_max_f32_e32 v1, v49, v49
	v_max_f32_e32 v5, 0, v1
	v_max_f32_e32 v1, v50, v50
	v_max_f32_e32 v6, 0, v1
	v_max_f32_e32 v1, v51, v51
	v_max_f32_e32 v7, 0, v1
	v_or_b32_e32 v8, 16, v0
	v_pk_mul_f32 v[4:5], v[4:5], v[4:5]
	v_pk_mul_f32 v[6:7], v[6:7], v[6:7]
	v_ashrrev_i32_e32 v9, 31, v8
	v_cvt_pk_bf16_f32 v4, v4, v5
	v_cvt_pk_bf16_f32 v5, v6, v7
	v_lshlrev_b64 v[6:7], 13, v[8:9]
	v_lshl_add_u64 v[6:7], v[2:3], 0, v[6:7]
	v_max_f32_e32 v1, v44, v44
	global_store_dwordx2 v[6:7], v[4:5], off
	v_max_f32_e32 v4, 0, v1
	v_max_f32_e32 v1, v45, v45
	v_max_f32_e32 v5, 0, v1
	v_max_f32_e32 v1, v46, v46
	v_max_f32_e32 v6, 0, v1
	v_max_f32_e32 v1, v47, v47
	v_max_f32_e32 v7, 0, v1
	v_or_b32_e32 v8, 32, v0
	v_pk_mul_f32 v[4:5], v[4:5], v[4:5]
	v_pk_mul_f32 v[6:7], v[6:7], v[6:7]
	v_ashrrev_i32_e32 v9, 31, v8
	v_cvt_pk_bf16_f32 v4, v4, v5
	v_cvt_pk_bf16_f32 v5, v6, v7
	v_lshlrev_b64 v[6:7], 13, v[8:9]
	v_lshl_add_u64 v[6:7], v[2:3], 0, v[6:7]
	v_max_f32_e32 v1, v40, v40
	global_store_dwordx2 v[6:7], v[4:5], off
	v_max_f32_e32 v4, 0, v1
	v_max_f32_e32 v1, v41, v41
	v_max_f32_e32 v5, 0, v1
	v_max_f32_e32 v1, v42, v42
	v_max_f32_e32 v6, 0, v1
	v_max_f32_e32 v1, v43, v43
	v_or_b32_e32 v0, 48, v0
	v_max_f32_e32 v7, 0, v1
	v_ashrrev_i32_e32 v1, 31, v0
	v_pk_mul_f32 v[4:5], v[4:5], v[4:5]
	v_pk_mul_f32 v[6:7], v[6:7], v[6:7]
	v_lshlrev_b64 v[0:1], 13, v[0:1]
	v_cvt_pk_bf16_f32 v4, v4, v5
	v_cvt_pk_bf16_f32 v5, v6, v7
	v_lshl_add_u64 v[0:1], v[2:3], 0, v[0:1]
	global_store_dwordx2 v[0:1], v[4:5], off

; #define GLOAD(ra, rb, koff)                                                        \
;   {                                                                                \
;     _Pragma("unroll") for (int j = 0; j < 4; j++) ra[j] = *(const u32x4*)(pa + j * sa32 + (koff));   \
;     _Pragma("unroll") for (int j = 0; j < NB_; j++) rb[j] = *(const u32x4*)(pbv[j] + (koff));         \
;   }
; template <int NT, bool PRE> ...
;     ...
;   const int wsw = ((tid & 7) ^ ((tid >> 4) & 7)) * 8;
;   const int rsw = (lane & 15) >> 1;
;     ...
;   if (!PRE) {
;     GLOAD(ra0, rb0, 0);
;     GLOAD(ra1, rb1, 64);
;   }
;   __syncthreads();
;   for (int k0 = 0; k0 < K; k0 += 128) {
;     LSTORE(ra0, rb0, 0);
;     __syncthreads();
;     GLOAD(ra0, rb0, min(k0 + 128, K - 128));
;     __builtin_amdgcn_sched_barrier(0);
;     COMPUTE(0);
;     LSTORE(ra1, rb1, 1);
;     __syncthreads();
;     GLOAD(ra1, rb1, min(k0 + 192, K - 64));
;     __builtin_amdgcn_sched_barrier(0);
;     COMPUTE(1);
;   }
; template <int NT>
; __device__ __forceinline__ void gemm_main(const u16* __restrict__ A, int lda, const u16* __restrict__ Bt, int ldb,
;                                           int K, int m0, int n0, f32x4 (&acc)[4][NT], u16* sA, u16* sB) {
;     ...
;   const u16* pa = A + (size_t)(m0 + (tid >> 3)) * lda + (tid & 7) * 8;
;   const u16* pbv[NT];
; #pragma unroll
;   for (int j = 0; j < NT; j++) pbv[j] = Bt + (size_t)(n0 + (tid >> 3) + 32 * j) * ldb + (tid & 7) * 8;
.LBB0_2292:
	s_and_b64 vcc, exec, s[46:47]
	s_cbranch_vccnz .LBB0_2296
	s_waitcnt vmcnt(17)
	v_mov_b32_e32 v40, v169
	v_readlane_b32 s2, v250, 30
	v_lshlrev_b32_e32 v41, 4, v40
	v_and_b32_e32 v130, 0x70, v41
	v_readlane_b32 s3, v250, 31
	v_ashrrev_i32_e32 v4, 3, v40
	v_lshrrev_b32_e32 v42, 4, v40
	v_lshl_add_u64 v[0:1], s[2:3], 0, v[130:131]
	v_readlane_b32 s2, v250, 50
	v_xor_b32_e32 v43, v42, v40
	v_lshlrev_b32_e32 v43, 4, v43
	v_add_u32_e32 v2, s2, v4
	v_ashrrev_i32_e32 v3, 31, v2
	v_lshlrev_b64 v[2:3], 13, v[2:3]
	v_readlane_b32 s2, v250, 49
	s_waitcnt vmcnt(16)
	v_lshl_add_u64 v[56:57], v[0:1], 0, v[2:3]
	v_and_b32_e32 v43, 0x70, v43
	v_add_u32_e32 v0, s2, v4
	v_ashrrev_i32_e32 v1, 31, v0
	v_readlane_b32 s2, v250, 28
	v_lshlrev_b64 v[0:1], 13, v[0:1]
	v_readlane_b32 s3, v250, 29
	v_bfe_u32 v45, v40, 1, 3
	v_and_b32_e32 v44, 15, v40
	v_lshl_add_u64 v[0:1], s[2:3], 0, v[0:1]
	v_lshl_add_u64 v[58:59], v[0:1], 0, v[130:131]
	v_add_co_u32_e32 v0, vcc, s19, v58
	s_movk_i32 s2, 0xff80
	s_nop 0
	v_addc_co_u32_e32 v1, vcc, 0, v59, vcc
	v_add_co_u32_e32 v2, vcc, s20, v58
	v_and_or_b32 v60, v41, s2, v43
	s_nop 0
	v_addc_co_u32_e32 v3, vcc, 0, v59, vcc
	v_add_co_u32_e32 v4, vcc, s21, v58
	v_bfe_u32 v41, v40, 4, 2
	s_nop 0
	v_addc_co_u32_e32 v5, vcc, 0, v59, vcc
	global_load_dwordx4 v[8:11], v[58:59], off
	global_load_dwordx4 v[20:23], v[58:59], off offset:128
	global_load_dwordx4 v[36:39], v[0:1], off
	global_load_dwordx4 v[24:27], v[0:1], off offset:128
	global_load_dwordx4 v[16:19], v[2:3], off
	global_load_dwordx4 v[12:15], v[2:3], off offset:128
	global_load_dwordx4 v[32:35], v[4:5], off
	global_load_dwordx4 v[28:31], v[4:5], off offset:128
	s_nop 0
	global_load_dwordx4 v[0:3], v[56:57], off
	global_load_dwordx4 v[4:7], v[56:57], off offset:128
	v_lshlrev_b32_e32 v43, 5, v40
	v_bitop3_b32 v42, v42, v45, 3 bitop3:0x6c
	v_lshlrev_b32_e32 v40, 6, v40
	v_bitop3_b32 v41, v41, v45, 4 bitop3:0x36
	v_lshlrev_b32_e32 v62, 4, v42
	v_and_b32_e32 v40, 0xffffe000, v40
	v_lshlrev_b32_e32 v63, 4, v41
	v_lshlrev_b32_e32 v44, 7, v44
	s_movk_i32 s3, 0x800
	v_or_b32_e32 v42, v62, v40
	v_or_b32_e32 v40, v63, v40
	v_mov_b32_e32 v48, 0
	v_and_or_b32 v61, v43, s3, v44
	v_add_u32_e32 v64, v42, v44
	v_add_u32_e32 v65, v40, v44
	v_mov_b32_e32 v49, v48
	v_mov_b32_e32 v50, v48
	v_mov_b32_e32 v51, v48
	v_mov_b32_e32 v52, v48
	v_mov_b32_e32 v53, v48
	v_mov_b32_e32 v54, v48
	v_mov_b32_e32 v55, v48
	v_mov_b32_e32 v44, v48
	v_mov_b32_e32 v45, v48
	v_mov_b32_e32 v46, v48
	v_mov_b32_e32 v47, v48
	v_mov_b32_e32 v40, v48
	v_mov_b32_e32 v41, v48
	v_mov_b32_e32 v42, v48
	v_mov_b32_e32 v43, v48
	s_barrier
	s_waitcnt vmcnt(8)
	ds_write_b128 v60, v[8:11]
	s_waitcnt vmcnt(7)
	ds_write_b128 v60, v[36:39] offset:4096
	s_waitcnt vmcnt(5)
	ds_write_b128 v60, v[16:19] offset:8192
	s_waitcnt vmcnt(3)
	ds_write_b128 v60, v[32:35] offset:12288
	s_waitcnt vmcnt(1)
	ds_write_b128 v60, v[0:3] offset:16384
	s_waitcnt vmcnt(0)
	s_waitcnt lgkmcnt(0)
	s_barrier
.LBB0_2294:
	s_add_i32 s3, s2, 0x100
	s_min_u32 s3, s3, 0xf80
	s_lshl_b32 s54, s3, 1
	v_add_u32_e32 v86, v61, v62
	v_add_u32_e32 v87, v61, v63
	ds_read_b128 v[66:69], v64
	ds_read_b128 v[70:73], v64 offset:2048
	ds_read_b128 v[74:77], v64 offset:4096
	ds_read_b128 v[78:81], v64 offset:6144
	ds_read_b128 v[82:85], v86 offset:16384
	ds_read_b128 v[88:91], v65
	ds_read_b128 v[92:95], v65 offset:2048
	ds_read_b128 v[96:99], v65 offset:4096
	ds_read_b128 v[100:103], v65 offset:6144
	ds_read_b128 v[104:107], v87 offset:16384
	v_lshl_add_u64 v[8:9], v[58:59], 0, s[54:55]
	v_add_co_u32_e32 v16, vcc, s19, v8
	v_lshl_add_u64 v[0:1], v[56:57], 0, s[54:55]
	s_nop 0
	v_addc_co_u32_e32 v17, vcc, 0, v9, vcc
	v_add_co_u32_e32 v18, vcc, s20, v8
	s_nop 0
	s_nop 0
	v_addc_co_u32_e32 v19, vcc, 0, v9, vcc
	v_add_co_u32_e32 v32, vcc, s21, v8
	s_nop 0
	s_nop 0
	v_addc_co_u32_e32 v33, vcc, 0, v9, vcc
	s_addk_i32 s2, 0x80
	s_setprio 1
	s_waitcnt lgkmcnt(5)
	v_mfma_f32_16x16x32_bf16 v[48:51], v[82:85], v[66:69], v[48:51]
	global_load_dwordx4 v[0:3], v[0:1], off
	s_nop 0
	v_mfma_f32_16x16x32_bf16 v[52:55], v[82:85], v[70:73], v[52:55]
	global_load_dwordx4 v[8:11], v[8:9], off
	s_nop 0
	v_mfma_f32_16x16x32_bf16 v[44:47], v[82:85], v[74:77], v[44:47]
	global_load_dwordx4 v[36:39], v[16:17], off
	s_nop 0
	global_load_dwordx4 v[16:19], v[18:19], off
	s_nop 0
	v_mfma_f32_16x16x32_bf16 v[40:43], v[82:85], v[78:81], v[40:43]
	global_load_dwordx4 v[32:35], v[32:33], off
	s_nop 0
	s_waitcnt lgkmcnt(0)
	v_mfma_f32_16x16x32_bf16 v[48:51], v[104:107], v[88:91], v[48:51]
	s_waitcnt vmcnt(9)
	ds_write_b128 v60, v[4:7] offset:49152
	v_mfma_f32_16x16x32_bf16 v[52:55], v[104:107], v[92:95], v[52:55]
	s_waitcnt vmcnt(8)
	ds_write_b128 v60, v[20:23] offset:32768
	s_waitcnt vmcnt(7)
	ds_write_b128 v60, v[24:27] offset:36864
	v_mfma_f32_16x16x32_bf16 v[44:47], v[104:107], v[96:99], v[44:47]
	s_waitcnt vmcnt(6)
	ds_write_b128 v60, v[12:15] offset:40960
	v_mfma_f32_16x16x32_bf16 v[40:43], v[104:107], v[100:103], v[40:43]
	s_waitcnt vmcnt(5)
	ds_write_b128 v60, v[28:31] offset:45056
	s_setprio 0
	s_waitcnt lgkmcnt(0)
	s_barrier
; #define GLOAD(ra, rb, koff)                                                        \
;   {                                                                                \
;     _Pragma("unroll") for (int j = 0; j < 4; j++) ra[j] = *(const u32x4*)(pa + j * sa32 + (koff));   \
;     _Pragma("unroll") for (int j = 0; j < NB_; j++) rb[j] = *(const u32x4*)(pbv[j] + (koff));         \
;   }
; template <int NT, bool PRE> ...
;     ...
;   if (!PRE) {
;     GLOAD(ra0, rb0, 0);
;     GLOAD(ra1, rb1, 64);
;   }
;   __syncthreads();
;   for (int k0 = 0; k0 < K; k0 += 128) {
;     LSTORE(ra0, rb0, 0);
;     __syncthreads();
;     GLOAD(ra0, rb0, min(k0 + 128, K - 128));
;     __builtin_amdgcn_sched_barrier(0);
;     COMPUTE(0);
;     LSTORE(ra1, rb1, 1);
;     __syncthreads();
;     GLOAD(ra1, rb1, min(k0 + 192, K - 64));
;     __builtin_amdgcn_sched_barrier(0);
;     COMPUTE(1);
;   }
; template <int EPI, int NT>
; __device__ __forceinline__ void gemm_tile_plain(char* ws, const u16* A, int lda, const u16* Bt, int K, int m0, int n0,
;                                                 u16* sA, u16* sB, int tq) {
;     ...
; #pragma unroll
;   for (int ni = 0; ni < NT; ni++) {
;     int col = GEMM_COL(ni, NT * 32);
; #pragma unroll
;     for (int mi = 0; mi < 4; mi++) {
;       int row = GEMM_ROW(mi);
;       f32x4 v = acc[mi][ni];
;       if (EPI == 0) {
;         *(float4*)((float*)(ws + O_F32) + (size_t)row * 1024 + col) = make_float4(v[0], v[1], v[2], v[3]);
	s_min_u32 s3, s2, 0xf00
	s_lshl_b32 s54, s3, 1
	ds_read_b128 v[66:69], v64 offset:32768
	ds_read_b128 v[70:73], v64 offset:34816
	ds_read_b128 v[74:77], v64 offset:36864
	ds_read_b128 v[78:81], v64 offset:38912
	ds_read_b128 v[82:85], v86 offset:49152
	ds_read_b128 v[88:91], v65 offset:32768
	ds_read_b128 v[92:95], v65 offset:34816
	ds_read_b128 v[96:99], v65 offset:36864
	ds_read_b128 v[100:103], v65 offset:38912
	ds_read_b128 v[104:107], v87 offset:49152
	v_lshl_add_u64 v[12:13], v[58:59], 0, s[54:55]
	v_add_co_u32_e32 v14, vcc, s19, v12
	v_lshl_add_u64 v[4:5], v[56:57], 0, s[54:55]
	s_nop 0
	v_addc_co_u32_e32 v15, vcc, 0, v13, vcc
	v_add_co_u32_e32 v28, vcc, s20, v12
	s_nop 0
	s_nop 0
	v_addc_co_u32_e32 v29, vcc, 0, v13, vcc
	v_add_co_u32_e32 v30, vcc, s21, v12
	s_nop 0
	s_nop 0
	v_addc_co_u32_e32 v31, vcc, 0, v13, vcc
	s_setprio 1
	s_waitcnt lgkmcnt(5)
	v_mfma_f32_16x16x32_bf16 v[48:51], v[82:85], v[66:69], v[48:51]
	global_load_dwordx4 v[4:7], v[4:5], off offset:384
	s_nop 0
	v_mfma_f32_16x16x32_bf16 v[52:55], v[82:85], v[70:73], v[52:55]
	global_load_dwordx4 v[20:23], v[12:13], off offset:384
	s_nop 0
	v_mfma_f32_16x16x32_bf16 v[44:47], v[82:85], v[74:77], v[44:47]
	global_load_dwordx4 v[24:27], v[14:15], off offset:384
	s_nop 0
	global_load_dwordx4 v[12:15], v[28:29], off offset:384
	s_nop 0
	v_mfma_f32_16x16x32_bf16 v[40:43], v[82:85], v[78:81], v[40:43]
	global_load_dwordx4 v[28:31], v[30:31], off offset:384
	s_nop 0
	s_waitcnt lgkmcnt(0)
	v_mfma_f32_16x16x32_bf16 v[48:51], v[104:107], v[88:91], v[48:51]
	s_waitcnt vmcnt(9)
	ds_write_b128 v60, v[0:3] offset:16384
	v_mfma_f32_16x16x32_bf16 v[52:55], v[104:107], v[92:95], v[52:55]
	s_waitcnt vmcnt(8)
	ds_write_b128 v60, v[8:11]
	s_waitcnt vmcnt(7)
	ds_write_b128 v60, v[36:39] offset:4096
	v_mfma_f32_16x16x32_bf16 v[44:47], v[104:107], v[96:99], v[44:47]
	s_waitcnt vmcnt(6)
	ds_write_b128 v60, v[16:19] offset:8192
	v_mfma_f32_16x16x32_bf16 v[40:43], v[104:107], v[100:103], v[40:43]
	s_waitcnt vmcnt(5)
	ds_write_b128 v60, v[32:35] offset:12288
	s_setprio 0
	s_waitcnt lgkmcnt(0)
	s_barrier
	s_cmpk_lt_u32 s2, 0xf00
	s_cbranch_scc1 .LBB0_2294
	v_add_u32_e32 v86, v61, v62
	v_add_u32_e32 v87, v61, v63
	ds_read_b128 v[66:69], v64
	ds_read_b128 v[70:73], v64 offset:2048
	ds_read_b128 v[74:77], v64 offset:4096
	ds_read_b128 v[78:81], v64 offset:6144
	ds_read_b128 v[82:85], v86 offset:16384
	ds_read_b128 v[88:91], v65
	ds_read_b128 v[92:95], v65 offset:2048
	ds_read_b128 v[96:99], v65 offset:4096
	ds_read_b128 v[100:103], v65 offset:6144
	ds_read_b128 v[104:107], v87 offset:16384
	s_addk_i32 s2, 0x80
	s_setprio 1
	s_waitcnt lgkmcnt(5)
	v_mfma_f32_16x16x32_bf16 v[48:51], v[82:85], v[66:69], v[48:51]
	v_mfma_f32_16x16x32_bf16 v[52:55], v[82:85], v[70:73], v[52:55]
	v_mfma_f32_16x16x32_bf16 v[44:47], v[82:85], v[74:77], v[44:47]
	v_mfma_f32_16x16x32_bf16 v[40:43], v[82:85], v[78:81], v[40:43]
	s_waitcnt lgkmcnt(0)
	v_mfma_f32_16x16x32_bf16 v[48:51], v[104:107], v[88:91], v[48:51]
	s_waitcnt vmcnt(4)
	ds_write_b128 v60, v[4:7] offset:49152
	v_mfma_f32_16x16x32_bf16 v[52:55], v[104:107], v[92:95], v[52:55]
	s_waitcnt vmcnt(3)
	ds_write_b128 v60, v[20:23] offset:32768
	s_waitcnt vmcnt(2)
	ds_write_b128 v60, v[24:27] offset:36864
	v_mfma_f32_16x16x32_bf16 v[44:47], v[104:107], v[96:99], v[44:47]
	s_waitcnt vmcnt(1)
	ds_write_b128 v60, v[12:15] offset:40960
	v_mfma_f32_16x16x32_bf16 v[40:43], v[104:107], v[100:103], v[40:43]
	s_waitcnt vmcnt(0)
	ds_write_b128 v60, v[28:31] offset:45056
	s_setprio 0
	s_waitcnt lgkmcnt(0)
	s_barrier
	ds_read_b128 v[66:69], v64 offset:32768
	ds_read_b128 v[70:73], v64 offset:34816
	ds_read_b128 v[74:77], v64 offset:36864
	ds_read_b128 v[78:81], v64 offset:38912
	ds_read_b128 v[82:85], v86 offset:49152
	ds_read_b128 v[88:91], v65 offset:32768
	ds_read_b128 v[92:95], v65 offset:34816
	ds_read_b128 v[96:99], v65 offset:36864
	ds_read_b128 v[100:103], v65 offset:38912
	ds_read_b128 v[104:107], v87 offset:49152
	s_setprio 1
	s_waitcnt lgkmcnt(5)
	v_mfma_f32_16x16x32_bf16 v[48:51], v[82:85], v[66:69], v[48:51]
	v_mfma_f32_16x16x32_bf16 v[52:55], v[82:85], v[70:73], v[52:55]
	v_mfma_f32_16x16x32_bf16 v[44:47], v[82:85], v[74:77], v[44:47]
	v_mfma_f32_16x16x32_bf16 v[40:43], v[82:85], v[78:81], v[40:43]
	s_waitcnt lgkmcnt(0)
	v_mfma_f32_16x16x32_bf16 v[48:51], v[104:107], v[88:91], v[48:51]
	v_mfma_f32_16x16x32_bf16 v[52:55], v[104:107], v[92:95], v[52:55]
	v_mfma_f32_16x16x32_bf16 v[44:47], v[104:107], v[96:99], v[44:47]
	v_mfma_f32_16x16x32_bf16 v[40:43], v[104:107], v[100:103], v[40:43]
	s_setprio 0
	s_waitcnt lgkmcnt(0)
	v_readlane_b32 s2, v250, 50
	s_waitcnt vmcnt(9)
	v_and_b32_e32 v0, 0xffffffc0, v148
	v_and_or_b32 v130, v147, 28, s2
	v_readlane_b32 s2, v250, 49
	v_lshl_add_u64 v[2:3], v[130:131], 2, s[0:1]
	s_mov_b64 s[0:1], 0xcb4b800
	v_and_or_b32 v1, v146, 15, s2
	v_add_u32_e32 v0, v1, v0
	v_ashrrev_i32_e32 v1, 31, v0
	v_lshl_add_u64 v[2:3], v[2:3], 0, s[0:1]
	s_waitcnt vmcnt(4)
	v_lshlrev_b64 v[4:5], 12, v[0:1]
	v_lshl_add_u64 v[4:5], v[2:3], 0, v[4:5]
	global_store_dwordx4 v[4:5], v[48:51], off
	v_or_b32_e32 v4, 16, v0
	v_ashrrev_i32_e32 v5, 31, v4
	v_lshlrev_b64 v[4:5], 12, v[4:5]
	v_lshl_add_u64 v[4:5], v[2:3], 0, v[4:5]
	global_store_dwordx4 v[4:5], v[52:55], off
	v_or_b32_e32 v4, 32, v0
	v_or_b32_e32 v0, 48, v0
	v_ashrrev_i32_e32 v5, 31, v4
	v_ashrrev_i32_e32 v1, 31, v0
	v_lshlrev_b64 v[4:5], 12, v[4:5]
	v_lshlrev_b64 v[0:1], 12, v[0:1]
	v_lshl_add_u64 v[4:5], v[2:3], 0, v[4:5]
	v_lshl_add_u64 v[0:1], v[2:3], 0, v[0:1]
	global_store_dwordx4 v[4:5], v[44:47], off
	global_store_dwordx4 v[0:1], v[40:43], off
